# loop-invariant load hoisting across work items: SGU layer-norm gain/bias loaded once per workgroup (v_fmac->v_fma keeps bias regs), plus k_mean staged once per (b,h) slot and SGU bias reuse
# speedup vs baseline: 1.0024x; 1.0024x over previous
; __device__ __forceinline__ float bflo(unsigned w) { return __uint_as_float(w << 16); }
; __device__ __forceinline__ float bfhi(unsigned w) { return __uint_as_float(w & 0xffff0000u); }
; __device__ __forceinline__ void sgu_item(LAS unsigned char* lds, const bf16_t* z, const float* lng, const float* lnb, const float* wsg, const float* bsg, bf16_t* cat, int b, int c, int g) {
;     ...
;     u32x4 vw[4], uw[4]; f32x4 w0[4], w1[4];
;     { const bf16_t* src = z + (row0 + p) * 5120 + 4096 + g * 128 + part * 32; const bf16_t* up = z + (row0 + p) * 5120 + 3072 + g * 128 + part * 32;
; #pragma unroll
;       for (int q = 0; q < 4; ++q) { vw[q] = *(const u32x4*)(src + q * 8); uw[q] = *(const u32x4*)(up + q * 8); }
;       const float* wp = wsg + ((size_t)g * 128 + t0 + lq) * 128 + quad * 8;
; #pragma unroll
;       for (int ks = 0; ks < 4; ++ks) { w0[ks] = *(const f32x4*)(wp + ks * 32); w1[ks] = *(const f32x4*)(wp + ks * 32 + 4); } }
;     {   float x[32];
; #pragma unroll
;         for (int q = 0; q < 4; ++q) { const u32x4 w = vw[q];
;             x[q * 8 + 0] = bflo(w.x); x[q * 8 + 1] = bfhi(w.x); x[q * 8 + 2] = bflo(w.y); x[q * 8 + 3] = bfhi(w.y); x[q * 8 + 4] = bflo(w.z); x[q * 8 + 5] = bfhi(w.z); x[q * 8 + 6] = bflo(w.w); x[q * 8 + 7] = bfhi(w.w); }
;         float s = 0.f;
; #pragma unroll
;         for (int d = 0; d < 32; ++d) s += x[d];
;         s += __shfl_xor(s, 1); s += __shfl_xor(s, 2);
;         const float mu = s * (1.0f / 128.0f); float q2 = 0.f;
; #pragma unroll
;         for (int d = 0; d < 32; ++d) { const float dd = x[d] - mu; q2 += dd * dd; }
;         q2 += __shfl_xor(q2, 1); q2 += __shfl_xor(q2, 2);
;         const float rstd = rsqrtf(q2 * (1.0f / 128.0f) + 1e-5f);
; #pragma unroll
;         for (int d = 0; d < 32; d += 2) { const int dc = g * 128 + part * 32 + d;
;             const float y0 = (x[d] - mu) * rstd * lng[dc] + lnb[dc], y1 = (x[d + 1] - mu) * rstd * lng[dc + 1] + lnb[dc + 1];
.Lmy_w_do:
	global_load_dwordx4 v[46:49], v[22:23], off offset:16
	global_load_dwordx4 v[42:45], v[22:23], off
	global_load_dwordx4 v[34:37], v[22:23], off offset:144
	global_load_dwordx4 v[38:41], v[22:23], off offset:128
	global_load_dwordx4 v[26:29], v[22:23], off offset:272
	global_load_dwordx4 v[30:33], v[22:23], off offset:256
	global_load_dwordx4 v[18:21], v[22:23], off offset:400
	s_nop 0
	global_load_dwordx4 v[22:25], v[22:23], off offset:384
	v_or_b32_e32 v152, s17, v67
	v_lshlrev_b32_e32 v152, 2, v152
	global_load_dwordx2 v[120:121], v152, s[10:11]
	global_load_dwordx2 v[154:155], v152, s[12:13]
	global_load_dwordx2 v[122:123], v152, s[10:11] offset:8
	global_load_dwordx2 v[156:157], v152, s[12:13] offset:8
	global_load_dwordx2 v[124:125], v152, s[10:11] offset:16
	global_load_dwordx2 v[158:159], v152, s[12:13] offset:16
	global_load_dwordx2 v[126:127], v152, s[10:11] offset:24
	global_load_dwordx2 v[160:161], v152, s[12:13] offset:24
	global_load_dwordx2 v[128:129], v152, s[10:11] offset:32
	global_load_dwordx2 v[162:163], v152, s[12:13] offset:32
	global_load_dwordx2 v[130:131], v152, s[10:11] offset:40
	global_load_dwordx2 v[164:165], v152, s[12:13] offset:40
	global_load_dwordx2 v[132:133], v152, s[10:11] offset:48
	global_load_dwordx2 v[166:167], v152, s[12:13] offset:48
	global_load_dwordx2 v[134:135], v152, s[10:11] offset:56
	global_load_dwordx2 v[168:169], v152, s[12:13] offset:56
	global_load_dwordx2 v[136:137], v152, s[10:11] offset:64
	global_load_dwordx2 v[170:171], v152, s[12:13] offset:64
	global_load_dwordx2 v[138:139], v152, s[10:11] offset:72
	global_load_dwordx2 v[172:173], v152, s[12:13] offset:72
	global_load_dwordx2 v[140:141], v152, s[10:11] offset:80
	global_load_dwordx2 v[174:175], v152, s[12:13] offset:80
	global_load_dwordx2 v[142:143], v152, s[10:11] offset:88
	global_load_dwordx2 v[176:177], v152, s[12:13] offset:88
	global_load_dwordx2 v[144:145], v152, s[10:11] offset:96
	global_load_dwordx2 v[178:179], v152, s[12:13] offset:96
	global_load_dwordx2 v[146:147], v152, s[10:11] offset:104
	global_load_dwordx2 v[180:181], v152, s[12:13] offset:104
	global_load_dwordx2 v[148:149], v152, s[10:11] offset:112
	global_load_dwordx2 v[182:183], v152, s[12:13] offset:112
	global_load_dwordx2 v[150:151], v152, s[10:11] offset:120
	global_load_dwordx2 v[184:185], v152, s[12:13] offset:120
.Lmy_w_skip:
	v_lshlrev_b32_e32 v62, 3, v71
	s_movk_i32 s2, 0x110
	s_cmp_lt_i32 s19, 0
	s_cmp_lg_u32 s3, 0
	s_cbranch_scc1 .Lmy_wa_r
	s_waitcnt vmcnt(39)
	s_branch .Lmy_wa_d
.Lmy_wa_r:
	s_waitcnt vmcnt(7)
.Lmy_wa_d:
	v_lshlrev_b32_e32 v58, 16, v54
	v_and_b32_e32 v92, 0xffff0000, v54
	v_add_f32_e32 v54, 0, v58
	v_lshlrev_b32_e32 v91, 16, v55
	v_add_f32_e32 v54, v54, v92
	v_and_b32_e32 v90, 0xffff0000, v55
	v_add_f32_e32 v54, v54, v91
	v_lshlrev_b32_e32 v89, 16, v56
	v_add_f32_e32 v54, v54, v90
	v_and_b32_e32 v88, 0xffff0000, v56
	v_add_f32_e32 v54, v54, v89
	v_lshlrev_b32_e32 v87, 16, v57
	v_add_f32_e32 v54, v54, v88
	v_and_b32_e32 v86, 0xffff0000, v57
	v_add_f32_e32 v54, v54, v87
	s_cmp_lg_u32 s3, 0
	s_cbranch_scc1 .Lmy_wb_r
	s_waitcnt vmcnt(36)
	s_branch .Lmy_wb_d
.Lmy_wb_r:
	s_waitcnt vmcnt(4)
.Lmy_wb_d:
	v_lshlrev_b32_e32 v85, 16, v72
	v_add_f32_e32 v54, v54, v86
	v_and_b32_e32 v84, 0xffff0000, v72
	v_add_f32_e32 v54, v54, v85
	v_lshlrev_b32_e32 v83, 16, v73
	v_add_f32_e32 v54, v54, v84
	v_and_b32_e32 v82, 0xffff0000, v73
	v_add_f32_e32 v54, v54, v83
	v_lshlrev_b32_e32 v81, 16, v74
	v_add_f32_e32 v54, v54, v82
	v_and_b32_e32 v80, 0xffff0000, v74
	v_add_f32_e32 v54, v54, v81
	v_lshlrev_b32_e32 v79, 16, v75
	v_add_f32_e32 v54, v54, v80
	v_and_b32_e32 v78, 0xffff0000, v75
	v_add_f32_e32 v54, v54, v79
	v_lshlrev_b32_e32 v77, 16, v94
	v_add_f32_e32 v54, v54, v78
	v_and_b32_e32 v76, 0xffff0000, v94
	v_add_f32_e32 v54, v54, v77
	v_lshlrev_b32_e32 v75, 16, v95
	v_add_f32_e32 v54, v54, v76
	v_and_b32_e32 v74, 0xffff0000, v95
	v_add_f32_e32 v54, v54, v75
	v_lshlrev_b32_e32 v73, 16, v96
	v_add_f32_e32 v54, v54, v74
	v_and_b32_e32 v56, 64, v233
	v_and_b32_e32 v72, 0xffff0000, v96
	v_add_f32_e32 v54, v54, v73
	v_xor_b32_e32 v55, 1, v233
	v_add_u32_e32 v56, 64, v56
	v_lshlrev_b32_e32 v65, 16, v97
	v_add_f32_e32 v54, v54, v72
	v_cmp_lt_i32_e32 vcc, v55, v56
	v_and_b32_e32 v64, 0xffff0000, v97
	v_add_f32_e32 v54, v54, v65
	v_cndmask_b32_e32 v55, v233, v55, vcc
	v_add_f32_e32 v54, v54, v64
	v_lshlrev_b32_e32 v59, 2, v55
	v_xor_b32_e32 v55, 2, v233
	v_lshlrev_b32_e32 v57, 16, v50
	v_cmp_lt_i32_e32 vcc, v55, v56
	v_and_b32_e32 v56, 0xffff0000, v50
	v_add_f32_e32 v50, v54, v57
	v_and_b32_e32 v60, 0xffff0000, v53
	v_lshlrev_b32_e32 v61, 16, v53
	v_lshlrev_b32_e32 v53, 16, v51
	v_add_f32_e32 v50, v50, v56
	v_and_b32_e32 v94, 0xffff0000, v52
	v_lshlrev_b32_e32 v95, 16, v52
	v_and_b32_e32 v52, 0xffff0000, v51
	v_add_f32_e32 v50, v50, v53
	v_add_f32_e32 v50, v50, v52
	v_add_f32_e32 v50, v50, v95
	v_add_f32_e32 v50, v50, v94
	v_add_f32_e32 v50, v50, v61
	v_add_f32_e32 v50, v50, v60
	ds_bpermute_b32 v51, v59, v50
	v_cndmask_b32_e32 v55, v233, v55, vcc
	v_lshlrev_b32_e32 v93, 2, v55
	s_waitcnt lgkmcnt(0)
	v_add_f32_e32 v50, v50, v51
	ds_bpermute_b32 v51, v93, v50
	s_waitcnt lgkmcnt(0)
; __device__ __forceinline__ unsigned cvt_pk_bf16(float lo, float hi) { unsigned r; asm volatile("v_cvt_pk_bf16_f32 %0, %1, %2" : "=v"(r) : "v"(lo), "v"(hi)); return r; }
; __device__ __forceinline__ void sgu_item(LAS unsigned char* lds, const bf16_t* z, const float* lng, const float* lnb, const float* wsg, const float* bsg, bf16_t* cat, int b, int c, int g) {
;     ...
;         s += __shfl_xor(s, 1); s += __shfl_xor(s, 2);
;         const float mu = s * (1.0f / 128.0f); float q2 = 0.f;
; #pragma unroll
;         for (int d = 0; d < 32; ++d) { const float dd = x[d] - mu; q2 += dd * dd; }
;         q2 += __shfl_xor(q2, 1); q2 += __shfl_xor(q2, 2);
;         const float rstd = rsqrtf(q2 * (1.0f / 128.0f) + 1e-5f);
; #pragma unroll
;         for (int d = 0; d < 32; d += 2) { const int dc = g * 128 + part * 32 + d;
;             const float y0 = (x[d] - mu) * rstd * lng[dc] + lnb[dc], y1 = (x[d + 1] - mu) * rstd * lng[dc + 1] + lnb[dc + 1];
;             const unsigned w = cvt_pk_bf16(y0, y1);
;             vnT[(part * 32 + d) * 136 + p] = (bf16_t)(w & 0xffffu); vnT[(part * 32 + d + 1) * 136 + p] = (bf16_t)(w >> 16); }
	v_add_f32_e32 v51, v50, v51
	v_fmac_f32_e32 v92, 0xbc000000, v51
	v_fmac_f32_e32 v58, 0xbc000000, v51
	v_mul_f32_e32 v96, v92, v92
	v_fmac_f32_e32 v96, v58, v58
	v_fmac_f32_e32 v91, 0xbc000000, v51
	v_fmac_f32_e32 v96, v91, v91
	v_fmac_f32_e32 v90, 0xbc000000, v51
	v_fmac_f32_e32 v96, v90, v90
	v_fmac_f32_e32 v89, 0xbc000000, v51
	v_fmac_f32_e32 v96, v89, v89
	v_fmac_f32_e32 v88, 0xbc000000, v51
	v_fmac_f32_e32 v96, v88, v88
	v_fmac_f32_e32 v87, 0xbc000000, v51
	v_fmac_f32_e32 v96, v87, v87
	v_fmac_f32_e32 v86, 0xbc000000, v51
	v_fmac_f32_e32 v96, v86, v86
	v_fmac_f32_e32 v85, 0xbc000000, v51
	v_fmac_f32_e32 v96, v85, v85
	v_fmac_f32_e32 v84, 0xbc000000, v51
	v_fmac_f32_e32 v96, v84, v84
	v_fmac_f32_e32 v83, 0xbc000000, v51
	v_fmac_f32_e32 v96, v83, v83
	v_fmac_f32_e32 v82, 0xbc000000, v51
	v_fmac_f32_e32 v96, v82, v82
	v_fmac_f32_e32 v81, 0xbc000000, v51
	v_fmac_f32_e32 v96, v81, v81
	v_fmac_f32_e32 v80, 0xbc000000, v51
	v_fmac_f32_e32 v96, v80, v80
	v_fmac_f32_e32 v79, 0xbc000000, v51
	v_fmac_f32_e32 v96, v79, v79
	v_fmac_f32_e32 v78, 0xbc000000, v51
	v_fmac_f32_e32 v96, v78, v78
	v_fmac_f32_e32 v77, 0xbc000000, v51
	v_fmac_f32_e32 v96, v77, v77
	v_fmac_f32_e32 v76, 0xbc000000, v51
	v_fmac_f32_e32 v96, v76, v76
	v_fmac_f32_e32 v75, 0xbc000000, v51
	v_fmac_f32_e32 v96, v75, v75
	v_fmac_f32_e32 v74, 0xbc000000, v51
	v_fmac_f32_e32 v96, v74, v74
	v_fmac_f32_e32 v73, 0xbc000000, v51
	v_fmac_f32_e32 v96, v73, v73
	v_fmac_f32_e32 v72, 0xbc000000, v51
	v_mul_f32_e32 v50, 0x3c000000, v51
	v_fmac_f32_e32 v96, v72, v72
	v_fmac_f32_e32 v65, 0xbc000000, v51
	v_fmac_f32_e32 v96, v65, v65
	v_fmac_f32_e32 v64, 0xbc000000, v51
	v_pk_add_f32 v[56:57], v[56:57], v[50:51] op_sel_hi:[1,0] neg_lo:[0,1] neg_hi:[0,1]
	v_fmac_f32_e32 v96, v64, v64
	v_pk_mul_f32 v[54:55], v[56:57], v[56:57]
	s_nop 0
	v_add_f32_e32 v51, v55, v96
	v_add_f32_e32 v51, v54, v51
	v_pk_add_f32 v[54:55], v[52:53], v[50:51] op_sel_hi:[1,0] neg_lo:[0,1] neg_hi:[0,1]
	s_nop 0
	v_pk_mul_f32 v[52:53], v[54:55], v[54:55]
	s_nop 0
	v_add_f32_e32 v51, v53, v51
	v_add_f32_e32 v51, v52, v51
	v_pk_add_f32 v[52:53], v[94:95], v[50:51] op_sel_hi:[1,0] neg_lo:[0,1] neg_hi:[0,1]
	s_nop 0
	v_pk_mul_f32 v[94:95], v[52:53], v[52:53]
	s_nop 0
	v_add_f32_e32 v51, v95, v51
	v_add_f32_e32 v94, v94, v51
	v_pk_add_f32 v[50:51], v[60:61], v[50:51] op_sel_hi:[1,0] neg_lo:[0,1] neg_hi:[0,1]
	s_nop 0
	v_pk_mul_f32 v[60:61], v[50:51], v[50:51]
	s_nop 0
	v_add_f32_e32 v61, v61, v94
	v_add_f32_e32 v60, v60, v61
	ds_bpermute_b32 v59, v59, v60
	s_waitcnt lgkmcnt(0)
	v_add_f32_e32 v59, v60, v59
	ds_bpermute_b32 v60, v93, v59
	s_waitcnt lgkmcnt(0)
	v_add_f32_e32 v59, v59, v60
	v_mov_b32_e32 v60, 0x3727c5ac
	v_fmamk_f32 v59, v59, 0x3c000000, v60
	v_cmp_gt_f32_e32 vcc, s33, v59
	v_mul_f32_e32 v60, 0x4b800000, v59
	s_nop 0
	v_cndmask_b32_e32 v59, v59, v60, vcc
	v_rsq_f32_e32 v59, v59
	s_nop 0
	v_mul_f32_e32 v60, 0x45800000, v59
	v_cndmask_b32_e32 v93, v59, v60, vcc
	v_or_b32_e32 v59, s17, v67
	v_lshlrev_b32_e32 v94, 2, v59
	v_mul_f32_e32 v95, v58, v93
	v_mul_f32_e32 v57, v57, v93
	v_mul_f32_e32 v56, v56, v93
	v_mul_f32_e32 v55, v55, v93
	v_mul_f32_e32 v54, v54, v93
	v_mul_f32_e32 v53, v53, v93
	v_mul_f32_e32 v52, v52, v93
	v_mul_f32_e32 v51, v51, v93
	v_mul_f32_e32 v50, v50, v93
	s_waitcnt vmcnt(30)
	v_fma_f32 v58, v120, v95, v154
	v_mul_f32_e32 v60, v92, v93
	v_fma_f32 v61, v121, v60, v155
	v_cvt_pk_bf16_f32 v59, v58, v61
	v_mul_u32_u24_e32 v58, 0x110, v67
	v_lshlrev_b32_e32 v60, 1, v66
	v_add3_u32 v58, 0, v58, v60
	ds_write_b16 v58, v59
	ds_write_b16_d16_hi v58, v59 offset:272
	v_mul_f32_e32 v59, v91, v93
	s_waitcnt vmcnt(28)
	v_fma_f32 v59, v122, v59, v156
	v_mul_f32_e32 v60, v90, v93
	v_fma_f32 v61, v123, v60, v157
	v_cvt_pk_bf16_f32 v59, v59, v61
	ds_write_b16 v58, v59 offset:544
	ds_write_b16_d16_hi v58, v59 offset:816
	v_mul_f32_e32 v59, v89, v93
	s_waitcnt vmcnt(26)
	v_fma_f32 v59, v124, v59, v158
	v_mul_f32_e32 v60, v88, v93
	v_fma_f32 v61, v125, v60, v159
	v_cvt_pk_bf16_f32 v59, v59, v61
	ds_write_b16 v58, v59 offset:1088
	ds_write_b16_d16_hi v58, v59 offset:1360
	v_mul_f32_e32 v59, v87, v93
	s_waitcnt vmcnt(24)
	v_fma_f32 v59, v126, v59, v160
	v_mul_f32_e32 v60, v86, v93
	v_fma_f32 v61, v127, v60, v161
	v_cvt_pk_bf16_f32 v59, v59, v61
	ds_write_b16 v58, v59 offset:1632
	ds_write_b16_d16_hi v58, v59 offset:1904
	v_mul_f32_e32 v59, v85, v93
	s_waitcnt vmcnt(22)
	v_fma_f32 v59, v128, v59, v162
	v_mul_f32_e32 v60, v84, v93
	v_fma_f32 v61, v129, v60, v163
	v_cvt_pk_bf16_f32 v59, v59, v61
	ds_write_b16 v58, v59 offset:2176
	ds_write_b16_d16_hi v58, v59 offset:2448
	v_mul_f32_e32 v59, v83, v93
	s_waitcnt vmcnt(20)
	v_fma_f32 v59, v130, v59, v164
	v_mul_f32_e32 v60, v82, v93
	v_fma_f32 v61, v131, v60, v165
	v_cvt_pk_bf16_f32 v59, v59, v61
	ds_write_b16 v58, v59 offset:2720
	ds_write_b16_d16_hi v58, v59 offset:2992
	v_mul_f32_e32 v59, v81, v93
	s_waitcnt vmcnt(18)
	v_fma_f32 v59, v132, v59, v166
	v_mul_f32_e32 v60, v80, v93
	v_fma_f32 v61, v133, v60, v167
	v_cvt_pk_bf16_f32 v59, v59, v61
	ds_write_b16 v58, v59 offset:3264
	ds_write_b16_d16_hi v58, v59 offset:3536
	v_mul_f32_e32 v59, v79, v93
	s_waitcnt vmcnt(16)
	v_fma_f32 v59, v134, v59, v168
	v_mul_f32_e32 v60, v78, v93
	v_fma_f32 v61, v135, v60, v169
	v_cvt_pk_bf16_f32 v59, v59, v61
	ds_write_b16 v58, v59 offset:3808
	ds_write_b16_d16_hi v58, v59 offset:4080
	v_mul_f32_e32 v59, v77, v93
	s_waitcnt vmcnt(14)
	v_fma_f32 v59, v136, v59, v170
	v_mul_f32_e32 v60, v76, v93
	v_fma_f32 v61, v137, v60, v171
	v_cvt_pk_bf16_f32 v59, v59, v61
	ds_write_b16 v58, v59 offset:4352
	ds_write_b16_d16_hi v58, v59 offset:4624
	v_mul_f32_e32 v59, v75, v93
	s_waitcnt vmcnt(12)
; __device__ __forceinline__ unsigned cvt_pk_bf16(float lo, float hi) { unsigned r; asm volatile("v_cvt_pk_bf16_f32 %0, %1, %2" : "=v"(r) : "v"(lo), "v"(hi)); return r; }
; __device__ __forceinline__ void sgu_item(LAS unsigned char* lds, const bf16_t* z, const float* lng, const float* lnb, const float* wsg, const float* bsg, bf16_t* cat, int b, int c, int g) {
;     ...
; #pragma unroll
;         for (int d = 0; d < 32; d += 2) { const int dc = g * 128 + part * 32 + d;
;             const float y0 = (x[d] - mu) * rstd * lng[dc] + lnb[dc], y1 = (x[d + 1] - mu) * rstd * lng[dc + 1] + lnb[dc + 1];
;             const unsigned w = cvt_pk_bf16(y0, y1);
;             vnT[(part * 32 + d) * 136 + p] = (bf16_t)(w & 0xffffu); vnT[(part * 32 + d + 1) * 136 + p] = (bf16_t)(w >> 16); }
;     }
;     bf16x8 Aw[4];
;     {   const int t = t0 + lq;
; #pragma unroll
;         for (int ks = 0; ks < 4; ++ks) { const int sidx = ks * 32 + quad * 8;
; #pragma unroll
;             for (int e = 0; e < 4; ++e) { if (sidx + e > t) w0[ks][e] = 0.f; if (sidx + 4 + e > t) w1[ks][e] = 0.f; }
;             Aw[ks] = __builtin_bit_cast(bf16x8, pack8(w0[ks], w1[ks])); } }
	v_fma_f32 v59, v59, v138, v172
	v_mul_f32_e32 v60, v74, v93
	v_fma_f32 v61, v60, v139, v173
	v_cvt_pk_bf16_f32 v59, v59, v61
	ds_write_b16 v58, v59 offset:4896
	ds_write_b16_d16_hi v58, v59 offset:5168
	v_mul_f32_e32 v59, v73, v93
	s_waitcnt vmcnt(10)
	v_fma_f32 v59, v59, v140, v174
	v_mul_f32_e32 v60, v72, v93
	v_fma_f32 v61, v60, v141, v175
	v_cvt_pk_bf16_f32 v59, v59, v61
	ds_write_b16 v58, v59 offset:5440
	ds_write_b16_d16_hi v58, v59 offset:5712
	v_mul_f32_e32 v59, v65, v93
	s_waitcnt vmcnt(8)
	v_fma_f32 v59, v59, v142, v176
	v_mul_f32_e32 v60, v64, v93
	v_fma_f32 v61, v60, v143, v177
	v_cvt_pk_bf16_f32 v59, v59, v61
	ds_write_b16 v58, v59 offset:5984
	ds_write_b16_d16_hi v58, v59 offset:6256
	s_waitcnt vmcnt(6)
	v_fma_f32 v57, v57, v144, v178
	v_fma_f32 v61, v56, v145, v179
	v_cvt_pk_bf16_f32 v56, v57, v61
	ds_write_b16 v58, v56 offset:6528
	ds_write_b16_d16_hi v58, v56 offset:6800
	s_waitcnt vmcnt(4)
	v_fma_f32 v55, v55, v146, v180
	v_fma_f32 v61, v54, v147, v181
	v_cvt_pk_bf16_f32 v54, v55, v61
	ds_write_b16 v58, v54 offset:7072
	ds_write_b16_d16_hi v58, v54 offset:7344
	s_waitcnt vmcnt(2)
	v_fma_f32 v53, v53, v148, v182
	v_fma_f32 v61, v52, v149, v183
	v_cvt_pk_bf16_f32 v52, v53, v61
	ds_write_b16 v58, v52 offset:7616
	ds_write_b16_d16_hi v58, v52 offset:7888
	s_waitcnt vmcnt(0)
	v_fma_f32 v51, v51, v150, v184
	v_fma_f32 v61, v50, v151, v185
	v_cvt_pk_bf16_f32 v50, v51, v61
	ds_write_b16 v58, v50 offset:8160
	ds_write_b16_d16_hi v58, v50 offset:8432
	s_cmp_lg_u32 s3, 0
	s_cbranch_scc1 .Lmy_aw_reuse
	v_bfi_b32 v50, -16, s19, v63
	v_cmp_gt_i32_e32 vcc, v62, v50
	v_mov_b32_e32 v52, s57
	s_nop 0
	v_cndmask_b32_e32 v54, v42, v52, vcc
	v_or_b32_e32 v52, 4, v62
	v_cndmask_b32_e32 v51, v44, v44, vcc
	v_cndmask_b32_e32 v53, v45, v45, vcc
	v_cmp_gt_i32_e32 vcc, v52, v50
	v_mov_b32_e32 v52, s57
	s_nop 0
	v_cndmask_b32_e32 v46, v46, v52, vcc
	v_cndmask_b32_e32 v49, v49, v49, vcc
	v_cndmask_b32_e32 v48, v48, v48, vcc
	v_cndmask_b32_e32 v47, v47, v47, vcc
	v_cmp_lt_i32_e32 vcc, v62, v50
	s_nop 1
	v_cndmask_b32_e32 v44, v51, v44, vcc
	v_or_b32_e32 v51, 5, v62
	v_cndmask_b32_e32 v42, v54, v42, vcc
	v_cndmask_b32_e32 v45, v53, v45, vcc
	v_cndmask_b32_e32 v43, 0, v43, vcc
	v_cmp_le_i32_e32 vcc, v51, v50
	v_or_b32_e32 v51, 2, v62
	v_cvt_pk_bf16_f32 v42, v42, v43
	s_nop 0
	v_cndmask_b32_e32 v47, 0, v47, vcc
	v_cmp_le_i32_e32 vcc, v51, v50
	v_or_b32_e32 v51, 6, v62
	s_nop 0
	v_cndmask_b32_e32 v44, 0, v44, vcc
	v_cmp_le_i32_e32 vcc, v51, v50
	v_or_b32_e32 v51, 3, v62
	s_nop 0
	v_cndmask_b32_e32 v48, 0, v48, vcc
	v_cmp_le_i32_e32 vcc, v51, v50
	v_or_b32_e32 v51, 7, v62
	s_nop 0
	v_cndmask_b32_e32 v45, 0, v45, vcc
	v_cmp_le_i32_e32 vcc, v51, v50
	v_cvt_pk_bf16_f32 v43, v44, v45
	v_cvt_pk_bf16_f32 v44, v46, v47
	v_or_b32_e32 v46, 32, v62
	s_nop 0
	v_cndmask_b32_e32 v49, 0, v49, vcc
	v_cmp_gt_i32_e32 vcc, v46, v50
	v_mov_b32_e32 v46, s57
	v_cvt_pk_bf16_f32 v45, v48, v49
	s_nop 0
	v_cndmask_b32_e32 v46, v38, v46, vcc
	v_or_b32_e32 v38, 36, v62
	v_cndmask_b32_e32 v41, v41, v41, vcc
	v_cndmask_b32_e32 v40, v40, v40, vcc
	v_cndmask_b32_e32 v39, v39, v39, vcc
	v_cmp_gt_i32_e32 vcc, v38, v50
	v_mov_b32_e32 v38, s57
	s_nop 0
	v_cndmask_b32_e32 v38, v34, v38, vcc
	v_cndmask_b32_e32 v34, v37, v37, vcc
	v_or_b32_e32 v37, 33, v62
	v_cndmask_b32_e32 v36, v36, v36, vcc
	v_cndmask_b32_e32 v35, v35, v35, vcc
	v_cmp_le_i32_e32 vcc, v37, v50
	s_nop 1
	v_cndmask_b32_e32 v37, 0, v39, vcc
	v_or_b32_e32 v39, 37, v62
	v_cmp_le_i32_e32 vcc, v39, v50
	s_nop 1
	v_cndmask_b32_e32 v39, 0, v35, vcc
	v_or_b32_e32 v35, 34, v62
	v_cmp_le_i32_e32 vcc, v35, v50
	s_nop 1
	v_cndmask_b32_e32 v35, 0, v40, vcc
	v_or_b32_e32 v40, 38, v62
	v_cmp_le_i32_e32 vcc, v40, v50
	s_nop 1
	v_cndmask_b32_e32 v40, 0, v36, vcc
	v_or_b32_e32 v36, 35, v62
	v_cmp_le_i32_e32 vcc, v36, v50
	s_nop 1
	v_cndmask_b32_e32 v36, 0, v41, vcc
	v_or_b32_e32 v41, 39, v62
	v_cmp_le_i32_e32 vcc, v41, v50
	s_nop 1
	v_cndmask_b32_e32 v41, 0, v34, vcc
	v_cvt_pk_bf16_f32 v34, v46, v37
	v_cvt_pk_bf16_f32 v35, v35, v36
	v_cvt_pk_bf16_f32 v36, v38, v39
	v_or_b32_e32 v38, 64, v62
	v_cmp_gt_i32_e32 vcc, v38, v50
	v_mov_b32_e32 v38, s57
	v_cvt_pk_bf16_f32 v37, v40, v41
	s_nop 0
	v_cndmask_b32_e32 v38, v30, v38, vcc
	v_or_b32_e32 v30, 0x44, v62
	v_cndmask_b32_e32 v33, v33, v33, vcc
	v_cndmask_b32_e32 v32, v32, v32, vcc
	v_cndmask_b32_e32 v31, v31, v31, vcc
	v_cmp_gt_i32_e32 vcc, v30, v50
	v_mov_b32_e32 v30, s57
	s_nop 0
	v_cndmask_b32_e32 v30, v26, v30, vcc
	v_cndmask_b32_e32 v26, v29, v29, vcc
	v_or_b32_e32 v29, 0x41, v62
	v_cndmask_b32_e32 v28, v28, v28, vcc
	v_cndmask_b32_e32 v27, v27, v27, vcc
	v_cmp_le_i32_e32 vcc, v29, v50
	s_nop 1
	v_cndmask_b32_e32 v29, 0, v31, vcc
	v_or_b32_e32 v31, 0x45, v62
	v_cmp_le_i32_e32 vcc, v31, v50
	s_nop 1
	v_cndmask_b32_e32 v31, 0, v27, vcc
	v_or_b32_e32 v27, 0x42, v62
	v_cmp_le_i32_e32 vcc, v27, v50
	s_nop 1
	v_cndmask_b32_e32 v27, 0, v32, vcc
	v_or_b32_e32 v32, 0x46, v62
	v_cmp_le_i32_e32 vcc, v32, v50
	s_nop 1
	v_cndmask_b32_e32 v32, 0, v28, vcc
	v_or_b32_e32 v28, 0x43, v62
	v_cmp_le_i32_e32 vcc, v28, v50
	s_nop 1
	v_cndmask_b32_e32 v28, 0, v33, vcc
	v_or_b32_e32 v33, 0x47, v62
	v_cmp_le_i32_e32 vcc, v33, v50
	s_nop 1
	v_cndmask_b32_e32 v33, 0, v26, vcc
	v_cvt_pk_bf16_f32 v26, v38, v29
	v_cvt_pk_bf16_f32 v27, v27, v28
	v_cvt_pk_bf16_f32 v28, v30, v31
	v_or_b32_e32 v30, 0x60, v62
	v_cmp_gt_i32_e32 vcc, v30, v50
	v_mov_b32_e32 v30, s57
	v_cvt_pk_bf16_f32 v29, v32, v33
	s_nop 0
	v_cndmask_b32_e32 v30, v22, v30, vcc
	v_or_b32_e32 v22, 0x64, v62
	v_cndmask_b32_e32 v25, v25, v25, vcc
	v_cndmask_b32_e32 v24, v24, v24, vcc
	v_cndmask_b32_e32 v23, v23, v23, vcc
	v_cmp_gt_i32_e32 vcc, v22, v50
	v_mov_b32_e32 v22, s57
	s_nop 0
	v_cndmask_b32_e32 v22, v18, v22, vcc
	v_cndmask_b32_e32 v18, v21, v21, vcc
	v_or_b32_e32 v21, 0x61, v62
	v_cndmask_b32_e32 v20, v20, v20, vcc
	v_cndmask_b32_e32 v19, v19, v19, vcc
	v_cmp_le_i32_e32 vcc, v21, v50
	s_nop 1
	v_cndmask_b32_e32 v21, 0, v23, vcc
	v_or_b32_e32 v23, 0x65, v62
	v_cmp_le_i32_e32 vcc, v23, v50
	s_nop 1
	v_cndmask_b32_e32 v23, 0, v19, vcc
	v_or_b32_e32 v19, 0x62, v62
	v_cmp_le_i32_e32 vcc, v19, v50
	s_nop 1
	v_cndmask_b32_e32 v19, 0, v24, vcc
	v_or_b32_e32 v24, 0x66, v62
	v_cmp_le_i32_e32 vcc, v24, v50
	s_nop 1
	v_cndmask_b32_e32 v24, 0, v20, vcc
	v_or_b32_e32 v20, 0x63, v62
	v_cmp_le_i32_e32 vcc, v20, v50
	s_nop 1
	v_cndmask_b32_e32 v20, 0, v25, vcc
	v_or_b32_e32 v25, 0x67, v62
	v_cmp_le_i32_e32 vcc, v25, v50
	s_nop 1
	v_cndmask_b32_e32 v25, 0, v18, vcc
	v_cvt_pk_bf16_f32 v18, v30, v21
	v_cvt_pk_bf16_f32 v19, v19, v20
	v_cvt_pk_bf16_f32 v20, v22, v23
	v_lshl_add_u32 v22, v71, 4, 0
	v_mad_u32_u24 v72, v70, s2, v22
	v_cvt_pk_bf16_f32 v21, v24, v25
	s_nop 0
	v_mov_b64_e32 v[206:207], v[18:19]
	v_mov_b64_e32 v[208:209], v[20:21]
	v_mov_b64_e32 v[210:211], v[26:27]
	v_mov_b64_e32 v[212:213], v[28:29]
	v_mov_b64_e32 v[214:215], v[34:35]
	v_mov_b64_e32 v[216:217], v[36:37]
	v_mov_b64_e32 v[218:219], v[42:43]
	v_mov_b64_e32 v[220:221], v[44:45]
	s_branch .Lmy_aw_join
